# attention steady-state loops: each step's two LDS-DMA requests issued at the top of the step (behind the slot-freeing barrier) instead of between the MFMA phases
# baseline (speedup 1.0000x reference)
.LBB0_375:
	v_add_u32_e32 v0, s8, v232
	ds_read_b64_tr_b16 v[192:193], v0 offset:24576
	ds_read_b64_tr_b16 v[194:195], v0 offset:25088
	v_lshl_add_u64 v[240:241], v[198:199], 0, s[40:41]
	s_add_i32 s8, s87, s97
	s_mov_b32 s9, m0
	s_mov_b32 m0, s8
	s_nop 0
	global_load_lds_dwordx4 v[240:241], off
	s_mov_b32 m0, s9
	v_lshl_add_u64 v[240:241], v[196:197], 0, s[40:41]
	s_add_i32 s8, s86, s95
	s_mov_b32 s9, m0
	s_mov_b32 m0, s8
	s_nop 0
	global_load_lds_dwordx4 v[240:241], off
	s_mov_b32 m0, s9
	s_waitcnt lgkmcnt(9)
	v_mfma_f32_32x32x16_bf16 v[112:127], v[188:191], v[156:159], v[48:63]
	v_add_f32_e32 v2, v80, v81
	v_add_f32_e32 v2, v82, v2
	v_add_f32_e32 v2, v83, v2
	v_add_f32_e32 v2, v84, v2
	v_add_f32_e32 v2, v85, v2
	v_cvt_pk_bf16_f32 v140, v80, v81
	v_cvt_pk_bf16_f32 v141, v82, v83
	ds_read_b64_tr_b16 v[80:81], v0 offset:28672
	ds_read_b64_tr_b16 v[82:83], v0 offset:29184
	s_waitcnt lgkmcnt(10)
	v_mfma_f32_32x32x16_bf16 v[96:111], v[184:187], v[156:159], v[48:63]
	v_add_f32_e32 v2, v86, v2
	v_add_f32_e32 v2, v87, v2
	v_add_f32_e32 v2, v88, v2
	v_add_f32_e32 v6, v89, v2
	v_cvt_pk_bf16_f32 v142, v84, v85
	v_cvt_pk_bf16_f32 v143, v86, v87
	ds_read_b64_tr_b16 v[2:3], v0 offset:25600
	ds_read_b64_tr_b16 v[4:5], v0 offset:26112
	s_waitcnt lgkmcnt(11)
	v_mfma_f32_32x32x16_bf16 v[112:127], v[180:183], v[152:155], v[112:127]
	v_add_f32_e32 v6, v90, v6
	v_add_f32_e32 v6, v91, v6
	v_add_f32_e32 v6, v92, v6
	v_add_f32_e32 v10, v93, v6
	v_cvt_pk_bf16_f32 v136, v88, v89
	v_cvt_pk_bf16_f32 v137, v90, v91
	ds_read_b64_tr_b16 v[6:7], v0 offset:29696
	ds_read_b64_tr_b16 v[8:9], v0 offset:30208
	s_waitcnt lgkmcnt(12)
	v_mfma_f32_32x32x16_bf16 v[96:111], v[176:179], v[152:155], v[96:111]
	v_add_f32_e32 v10, v94, v10
	v_add_f32_e32 v10, v95, v10
	v_add_f32_e32 v10, v64, v10
	v_add_f32_e32 v14, v65, v10
	v_cvt_pk_bf16_f32 v138, v92, v93
	v_cvt_pk_bf16_f32 v139, v94, v95
	ds_read_b64_tr_b16 v[10:11], v0 offset:26624
	ds_read_b64_tr_b16 v[12:13], v0 offset:27136
	s_waitcnt lgkmcnt(13)
	v_mfma_f32_32x32x16_bf16 v[112:127], v[172:175], v[148:151], v[112:127]
	v_add_f32_e32 v14, v66, v14
	v_add_f32_e32 v14, v67, v14
	v_add_f32_e32 v14, v68, v14
	v_add_f32_e32 v14, v69, v14
	v_cvt_pk_bf16_f32 v132, v64, v65
	v_cvt_pk_bf16_f32 v133, v66, v67
	ds_read_b64_tr_b16 v[64:65], v0 offset:30720
	ds_read_b64_tr_b16 v[66:67], v0 offset:31232
	s_waitcnt lgkmcnt(14)
	v_mfma_f32_32x32x16_bf16 v[96:111], v[168:171], v[148:151], v[96:111]
	v_add_f32_e32 v14, v70, v14
	v_add_f32_e32 v14, v71, v14
	v_add_f32_e32 v14, v72, v14
	v_add_f32_e32 v14, v73, v14
	v_cvt_pk_bf16_f32 v134, v68, v69
	v_cvt_pk_bf16_f32 v135, v70, v71
	ds_read_b64_tr_b16 v[68:69], v0 offset:27648
	ds_read_b64_tr_b16 v[70:71], v0 offset:28160
	s_waitcnt lgkmcnt(14)
	v_mfma_f32_32x32x16_bf16 v[112:127], v[164:167], v[144:147], v[112:127]
	v_add_f32_e32 v14, v74, v14
	v_add_f32_e32 v14, v75, v14
	v_add_f32_e32 v14, v76, v14
	v_add_f32_e32 v14, v77, v14
	v_cvt_pk_bf16_f32 v128, v72, v73
	v_cvt_pk_bf16_f32 v129, v74, v75
	ds_read_b64_tr_b16 v[72:73], v0 offset:31744
	ds_read_b64_tr_b16 v[74:75], v0 offset:32256
	v_mfma_f32_32x32x16_bf16 v[96:111], v[160:163], v[144:147], v[96:111]
	v_add_f32_e32 v0, v78, v14
	v_add_f32_e32 v0, v79, v0
	v_add_f32_e32 v0, 0, v0
	v_cvt_pk_bf16_f32 v130, v76, v77
	v_cvt_pk_bf16_f32 v131, v78, v79
	v_max_f32_e32 v14, v113, v113
	v_max_f32_e32 v15, v112, v112
	v_max_f32_e32 v14, v15, v14
	v_max3_f32 v15, v114, v115, v97
	v_max3_f32 v14, v14, v96, v98
	v_max3_f32 v14, v14, v99, v116
	v_max3_f32 v15, v15, v118, v119
	v_max3_f32 v14, v14, v117, v100
	v_max3_f32 v15, v15, v102, v103
	v_max3_f32 v14, v14, v101, v120
	v_max3_f32 v15, v15, v122, v123
	v_max3_f32 v14, v14, v121, v104
	v_max3_f32 v15, v15, v106, v107
	v_max3_f32 v14, v14, v105, v124
	v_max3_f32 v15, v15, v126, v127
	v_max3_f32 v76, v14, v125, v108
	v_max3_f32 v15, v15, v110, v111
	v_add_f32_e32 v14, v234, v0
	v_max3_f32 v0, v76, v109, v15
	v_mov_b32_e32 v15, v0
	s_nop 1
	v_permlane32_swap_b32_e32 v0, v15
	v_max_f32_e32 v15, v15, v15
	v_max_f32_e32 v0, v0, v0
	v_max_f32_e32 v0, v0, v15
	v_cmp_lt_f32_e32 vcc, s21, v0
	s_cmp_lg_u64 vcc, 0
	s_cselect_b64 s[8:9], -1, 0
	s_cbranch_vccnz .LBB0_383

.LBB0_378:
	s_add_i32 s8, s86, 0x2000
	s_cmpk_lg_i32 s86, 0x4000
	s_cselect_b32 s99, s8, 0
	v_add_u32_e32 v15, s87, v232
	ds_read_b64_tr_b16 v[160:161], v15 offset:24576
	ds_read_b64_tr_b16 v[162:163], v15 offset:25088
	s_add_i32 s8, s86, s97
	s_mov_b32 s9, m0
	s_mov_b32 m0, s8
	s_nop 0
	global_load_lds_dwordx4 v[198:199], off
	s_mov_b32 m0, s9
	s_add_i32 s8, s99, s95
	s_mov_b32 s9, m0
	s_mov_b32 m0, s8
	s_nop 0
	global_load_lds_dwordx4 v[196:197], off
	s_mov_b32 m0, s9
	s_waitcnt lgkmcnt(9)
	v_mfma_f32_32x32x16_bf16 v[80:95], v[76:79], v[156:159], v[48:63]
	v_add_f32_e32 v2, v112, v113
	v_add_f32_e32 v2, v114, v2
	v_add_f32_e32 v2, v115, v2
	v_add_f32_e32 v2, v116, v2
	v_add_f32_e32 v2, v117, v2
	v_cvt_pk_bf16_f32 v140, v112, v113
	v_cvt_pk_bf16_f32 v141, v114, v115
	ds_read_b64_tr_b16 v[112:113], v15 offset:28672
	ds_read_b64_tr_b16 v[114:115], v15 offset:29184
	s_waitcnt lgkmcnt(10)
	v_mfma_f32_32x32x16_bf16 v[64:79], v[184:187], v[156:159], v[48:63]
	v_add_f32_e32 v2, v118, v2
	v_add_f32_e32 v2, v119, v2
	v_add_f32_e32 v2, v120, v2
	v_add_f32_e32 v6, v121, v2
	v_cvt_pk_bf16_f32 v142, v116, v117
	v_cvt_pk_bf16_f32 v143, v118, v119
	ds_read_b64_tr_b16 v[2:3], v15 offset:25600
	ds_read_b64_tr_b16 v[4:5], v15 offset:26112
	s_waitcnt lgkmcnt(11)
	v_mfma_f32_32x32x16_bf16 v[80:95], v[188:191], v[152:155], v[80:95]
	v_add_f32_e32 v6, v122, v6
	v_add_f32_e32 v6, v123, v6
	v_add_f32_e32 v6, v124, v6
	v_add_f32_e32 v10, v125, v6
	v_cvt_pk_bf16_f32 v136, v120, v121
	v_cvt_pk_bf16_f32 v137, v122, v123
	ds_read_b64_tr_b16 v[6:7], v15 offset:29696
	ds_read_b64_tr_b16 v[8:9], v15 offset:30208
	s_waitcnt lgkmcnt(12)
	v_mfma_f32_32x32x16_bf16 v[64:79], v[180:183], v[152:155], v[64:79]
	v_add_f32_e32 v10, v126, v10
	v_add_f32_e32 v10, v127, v10
	v_add_f32_e32 v10, v96, v10
	v_add_f32_e32 v116, v97, v10
	v_cvt_pk_bf16_f32 v138, v124, v125
	v_cvt_pk_bf16_f32 v139, v126, v127
	ds_read_b64_tr_b16 v[10:11], v15 offset:26624
	ds_read_b64_tr_b16 v[12:13], v15 offset:27136
	s_waitcnt lgkmcnt(13)
	v_mfma_f32_32x32x16_bf16 v[80:95], v[176:179], v[148:151], v[80:95]
	v_add_f32_e32 v116, v98, v116
	v_add_f32_e32 v116, v99, v116
	v_add_f32_e32 v116, v100, v116
	v_add_f32_e32 v116, v101, v116
	v_cvt_pk_bf16_f32 v132, v96, v97
	v_cvt_pk_bf16_f32 v133, v98, v99
	ds_read_b64_tr_b16 v[96:97], v15 offset:30720
	ds_read_b64_tr_b16 v[98:99], v15 offset:31232
	s_waitcnt lgkmcnt(14)
	v_mfma_f32_32x32x16_bf16 v[64:79], v[172:175], v[148:151], v[64:79]
	v_add_f32_e32 v116, v102, v116
	v_add_f32_e32 v116, v103, v116
	v_add_f32_e32 v116, v104, v116
	v_add_f32_e32 v116, v105, v116
	v_cvt_pk_bf16_f32 v134, v100, v101
	v_cvt_pk_bf16_f32 v135, v102, v103
	ds_read_b64_tr_b16 v[100:101], v15 offset:27648
	ds_read_b64_tr_b16 v[102:103], v15 offset:28160
	s_waitcnt lgkmcnt(14)
	v_mfma_f32_32x32x16_bf16 v[80:95], v[168:171], v[144:147], v[80:95]
	v_add_f32_e32 v116, v106, v116
	v_add_f32_e32 v116, v107, v116
	v_add_f32_e32 v116, v108, v116
	v_add_f32_e32 v116, v109, v116
	v_cvt_pk_bf16_f32 v128, v104, v105
	v_cvt_pk_bf16_f32 v129, v106, v107
	ds_read_b64_tr_b16 v[104:105], v15 offset:31744
	ds_read_b64_tr_b16 v[106:107], v15 offset:32256
	v_mfma_f32_32x32x16_bf16 v[64:79], v[164:167], v[144:147], v[64:79]
	v_add_f32_e32 v15, v110, v116
	v_add_f32_e32 v15, v111, v15
	v_add_f32_e32 v15, 0, v15
	v_cvt_pk_bf16_f32 v130, v108, v109
	v_cvt_pk_bf16_f32 v131, v110, v111
	v_max_f32_e32 v108, v81, v81
	v_max_f32_e32 v109, v80, v80
	v_max_f32_e32 v108, v109, v108
	s_nop 3
	v_max3_f32 v109, v82, v83, v65
	v_max3_f32 v108, v108, v64, v66
	v_max3_f32 v108, v108, v67, v84
	v_max3_f32 v109, v109, v86, v87
	v_max3_f32 v108, v108, v85, v68
	v_max3_f32 v109, v109, v70, v71
	v_max3_f32 v108, v108, v69, v88
	v_max3_f32 v109, v109, v90, v91
	v_max3_f32 v108, v108, v89, v72
	v_max3_f32 v109, v109, v74, v75
	v_max3_f32 v108, v108, v73, v92
	v_max3_f32 v109, v109, v94, v95
	v_max3_f32 v108, v108, v93, v76
	v_max3_f32 v109, v109, v78, v79
	v_add_f32_e32 v234, v14, v15
	v_max3_f32 v14, v108, v77, v109
	v_mov_b32_e32 v15, v14
	s_nop 1
	v_permlane32_swap_b32_e32 v14, v15
	v_max_f32_e32 v15, v15, v15
	v_max_f32_e32 v14, v14, v14
	v_max_f32_e32 v14, v14, v15
	v_cmp_lt_f32_e32 vcc, s21, v14
	s_cmp_lg_u64 vcc, 0
	s_cselect_b64 s[8:9], -1, 0
	s_cbranch_vccnz .LBB0_386

.Lj1_375:
	v_add_u32_e32 v0, s8, v232
	ds_read_b64_tr_b16 v[192:193], v0 offset:24576
	ds_read_b64_tr_b16 v[194:195], v0 offset:25088
	v_lshl_add_u64 v[240:241], v[198:199], 0, s[40:41]
	s_add_i32 s8, s87, s97
	s_mov_b32 s9, m0
	s_mov_b32 m0, s8
	s_nop 0
	global_load_lds_dwordx4 v[240:241], off
	s_mov_b32 m0, s9
	v_lshl_add_u64 v[240:241], v[196:197], 0, s[40:41]
	s_add_i32 s8, s86, s95
	s_mov_b32 s9, m0
	s_mov_b32 m0, s8
	s_nop 0
	global_load_lds_dwordx4 v[240:241], off
	s_mov_b32 m0, s9
	s_waitcnt lgkmcnt(9)
	v_mfma_f32_32x32x16_bf16 v[112:127], v[188:191], v[156:159], v[48:63]
	v_cvt_pk_bf16_f32 v140, v80, v81
	v_cvt_pk_bf16_f32 v141, v82, v83
	ds_read_b64_tr_b16 v[80:81], v0 offset:28672
	ds_read_b64_tr_b16 v[82:83], v0 offset:29184
	s_waitcnt lgkmcnt(10)
	v_mfma_f32_32x32x16_bf16 v[96:111], v[184:187], v[156:159], v[48:63]
	v_cvt_pk_bf16_f32 v142, v84, v85
	v_cvt_pk_bf16_f32 v143, v86, v87
	ds_read_b64_tr_b16 v[2:3], v0 offset:25600
	ds_read_b64_tr_b16 v[4:5], v0 offset:26112
	s_waitcnt lgkmcnt(11)
	v_mfma_f32_32x32x16_bf16 v[112:127], v[180:183], v[152:155], v[112:127]
	v_cvt_pk_bf16_f32 v136, v88, v89
	v_cvt_pk_bf16_f32 v137, v90, v91
	ds_read_b64_tr_b16 v[6:7], v0 offset:29696
	ds_read_b64_tr_b16 v[8:9], v0 offset:30208
	s_waitcnt lgkmcnt(12)
	v_mfma_f32_32x32x16_bf16 v[96:111], v[176:179], v[152:155], v[96:111]
	v_cvt_pk_bf16_f32 v138, v92, v93
	v_cvt_pk_bf16_f32 v139, v94, v95
	ds_read_b64_tr_b16 v[10:11], v0 offset:26624
	ds_read_b64_tr_b16 v[12:13], v0 offset:27136
	s_waitcnt lgkmcnt(13)
	v_mfma_f32_32x32x16_bf16 v[112:127], v[172:175], v[148:151], v[112:127]
	v_cvt_pk_bf16_f32 v132, v64, v65
	v_cvt_pk_bf16_f32 v133, v66, v67
	ds_read_b64_tr_b16 v[64:65], v0 offset:30720
	ds_read_b64_tr_b16 v[66:67], v0 offset:31232
	s_waitcnt lgkmcnt(14)
	v_mfma_f32_32x32x16_bf16 v[96:111], v[168:171], v[148:151], v[96:111]
	v_cvt_pk_bf16_f32 v134, v68, v69
	v_cvt_pk_bf16_f32 v135, v70, v71
	ds_read_b64_tr_b16 v[68:69], v0 offset:27648
	ds_read_b64_tr_b16 v[70:71], v0 offset:28160
	s_waitcnt lgkmcnt(14)
	v_mfma_f32_32x32x16_bf16 v[112:127], v[164:167], v[144:147], v[112:127]
	v_cvt_pk_bf16_f32 v128, v72, v73
	v_cvt_pk_bf16_f32 v129, v74, v75
	ds_read_b64_tr_b16 v[72:73], v0 offset:31744
	ds_read_b64_tr_b16 v[74:75], v0 offset:32256
	v_mfma_f32_32x32x16_bf16 v[96:111], v[160:163], v[144:147], v[96:111]
	v_cvt_pk_bf16_f32 v130, v76, v77
	v_cvt_pk_bf16_f32 v131, v78, v79
	s_nop 1
	s_mov_b64 s[8:9], 0

.Lj1_378:
	s_add_i32 s8, s86, 0x2000
	s_cmpk_lg_i32 s86, 0x4000
	s_cselect_b32 s99, s8, 0
	v_add_u32_e32 v15, s87, v232
	ds_read_b64_tr_b16 v[160:161], v15 offset:24576
	ds_read_b64_tr_b16 v[162:163], v15 offset:25088
	s_add_i32 s8, s86, s97
	s_mov_b32 s9, m0
	s_mov_b32 m0, s8
	s_nop 0
	global_load_lds_dwordx4 v[198:199], off
	s_mov_b32 m0, s9
	s_add_i32 s8, s99, s95
	s_mov_b32 s9, m0
	s_mov_b32 m0, s8
	s_nop 0
	global_load_lds_dwordx4 v[196:197], off
	s_mov_b32 m0, s9
	s_waitcnt lgkmcnt(9)
	v_mfma_f32_32x32x16_bf16 v[80:95], v[76:79], v[156:159], v[48:63]
	v_cvt_pk_bf16_f32 v140, v112, v113
	v_cvt_pk_bf16_f32 v141, v114, v115
	ds_read_b64_tr_b16 v[112:113], v15 offset:28672
	ds_read_b64_tr_b16 v[114:115], v15 offset:29184
	s_waitcnt lgkmcnt(10)
	v_mfma_f32_32x32x16_bf16 v[64:79], v[184:187], v[156:159], v[48:63]
	v_cvt_pk_bf16_f32 v142, v116, v117
	v_cvt_pk_bf16_f32 v143, v118, v119
	ds_read_b64_tr_b16 v[2:3], v15 offset:25600
	ds_read_b64_tr_b16 v[4:5], v15 offset:26112
	s_waitcnt lgkmcnt(11)
	v_mfma_f32_32x32x16_bf16 v[80:95], v[188:191], v[152:155], v[80:95]
	v_cvt_pk_bf16_f32 v136, v120, v121
	v_cvt_pk_bf16_f32 v137, v122, v123
	ds_read_b64_tr_b16 v[6:7], v15 offset:29696
	ds_read_b64_tr_b16 v[8:9], v15 offset:30208
	s_waitcnt lgkmcnt(12)
	v_mfma_f32_32x32x16_bf16 v[64:79], v[180:183], v[152:155], v[64:79]
	v_cvt_pk_bf16_f32 v138, v124, v125
	v_cvt_pk_bf16_f32 v139, v126, v127
	ds_read_b64_tr_b16 v[10:11], v15 offset:26624
	ds_read_b64_tr_b16 v[12:13], v15 offset:27136
	s_waitcnt lgkmcnt(13)
	v_mfma_f32_32x32x16_bf16 v[80:95], v[176:179], v[148:151], v[80:95]
	v_cvt_pk_bf16_f32 v132, v96, v97
	v_cvt_pk_bf16_f32 v133, v98, v99
	ds_read_b64_tr_b16 v[96:97], v15 offset:30720
	ds_read_b64_tr_b16 v[98:99], v15 offset:31232
	s_waitcnt lgkmcnt(14)
	v_mfma_f32_32x32x16_bf16 v[64:79], v[172:175], v[148:151], v[64:79]
	v_cvt_pk_bf16_f32 v134, v100, v101
	v_cvt_pk_bf16_f32 v135, v102, v103
	ds_read_b64_tr_b16 v[100:101], v15 offset:27648
	ds_read_b64_tr_b16 v[102:103], v15 offset:28160
	s_waitcnt lgkmcnt(14)
	v_mfma_f32_32x32x16_bf16 v[80:95], v[168:171], v[144:147], v[80:95]
	v_cvt_pk_bf16_f32 v128, v104, v105
	v_cvt_pk_bf16_f32 v129, v106, v107
	ds_read_b64_tr_b16 v[104:105], v15 offset:31744
	ds_read_b64_tr_b16 v[106:107], v15 offset:32256
	v_mfma_f32_32x32x16_bf16 v[64:79], v[164:167], v[144:147], v[64:79]
	v_cvt_pk_bf16_f32 v130, v108, v109
	v_cvt_pk_bf16_f32 v131, v110, v111
	s_nop 3
	s_nop 1
	s_mov_b64 s[8:9], 0
